# norm phase: two latent rows per wave requested ahead of the row being processed (two prefetch buffers used alternately) instead of one
# speedup vs baseline: 1.0028x; 1.0028x over previous
.LBB0_179:
	v_lshrrev_b32_e32 v96, 6, v138
	v_and_b32_e32 v98, 63, v138
	v_readfirstlane_b32 s8, v96
	v_lshlrev_b32_e32 v104, 4, v98
	v_lshlrev_b32_e32 v105, 3, v98
	v_xor_b32_e32 v106, 32, v98
	v_lshlrev_b32_e32 v106, 2, v106
	v_xor_b32_e32 v107, 16, v98
	v_lshlrev_b32_e32 v107, 2, v107
	v_xor_b32_e32 v108, 8, v98
	v_lshlrev_b32_e32 v108, 2, v108
	v_xor_b32_e32 v110, 4, v98
	v_lshlrev_b32_e32 v110, 2, v110
	v_xor_b32_e32 v111, 2, v98
	v_lshlrev_b32_e32 v111, 2, v111
	v_xor_b32_e32 v112, 1, v98
	v_lshlrev_b32_e32 v112, 2, v112
	v_readlane_b32 s2, v207, 52
	v_readlane_b32 s3, v207, 53
	s_nop 0
	s_load_dword s18, s[2:3], 0x0
	s_lshl_b32 s9, s96, 2
	s_add_u32 s9, s9, s8
	s_waitcnt lgkmcnt(0)
	s_lshl_b32 s18, s18, 2
	s_lshl_b32 s2, s50, 12
	v_readlane_b32 s76, v207, 16
	v_readlane_b32 s77, v207, 17
	s_add_u32 s76, s76, s2
	s_addc_u32 s77, s77, 0
	s_mul_i32 s2, s50, 0x9000
	s_add_u32 s2, s2, 0x4000
	s_add_u32 s78, s94, s2
	s_addc_u32 s79, s95, 0
	s_add_u32 s80, s94, 0x1100000
	s_addc_u32 s81, s95, 0
	v_readlane_b32 s82, v207, 4
	v_readlane_b32 s83, v207, 5
	s_add_u32 s84, s94, 0xa700000
	s_addc_u32 s85, s95, 0
	v_readlane_b32 s86, v207, 8
	v_readlane_b32 s87, v207, 9
	s_add_u32 s88, s94, 0xa500000
	s_addc_u32 s89, s95, 0
	s_add_u32 s90, s94, 0xc700000
	s_addc_u32 s91, s95, 0
	global_load_dwordx4 v[16:19], v104, s[76:77]
	global_load_dwordx4 v[20:23], v104, s[76:77] offset:1024
	global_load_dwordx4 v[24:27], v104, s[76:77] offset:2048
	global_load_dwordx4 v[28:31], v104, s[76:77] offset:3072
	s_mov_b32 s16, -1
	s_mov_b32 s76, -1
	s_mov_b32 s77, -1

.Lnm_have_mv:
	s_cmpk_lt_u32 s9, 0x4000
	s_cbranch_scc0 .Lnm_ctxrow
	s_cmp_eq_u32 s50, 0
	s_cbranch_scc0 .Lnm_bf16row
	s_cmp_eq_u32 s76, s9
	s_cbranch_scc1 .Lnm_f32_b0w
	s_cmp_eq_u32 s77, s9
	s_cbranch_scc1 .Lnm_f32_b1w
	s_lshl_b32 s2, s9, 12
	s_add_u32 s12, s82, s2
	s_addc_u32 s13, s83, 0
	global_load_dwordx4 v[208:211], v104, s[12:13] nt
	global_load_dwordx4 v[212:215], v104, s[12:13] offset:1024 nt
	global_load_dwordx4 v[216:219], v104, s[12:13] offset:2048 nt
	global_load_dwordx4 v[220:223], v104, s[12:13] offset:3072 nt
	s_mov_b32 s76, s9
	s_waitcnt vmcnt(0)
	s_branch .Lnm_f32_b0
.Lnm_f32_b0w:
	s_waitcnt vmcnt(8)
.Lnm_f32_b0:
	v_mov_b32_e32 v0, v208
	v_mov_b32_e32 v1, v209
	v_mov_b32_e32 v2, v210
	v_mov_b32_e32 v3, v211
	v_mov_b32_e32 v4, v212
	v_mov_b32_e32 v5, v213
	v_mov_b32_e32 v6, v214
	v_mov_b32_e32 v7, v215
	v_mov_b32_e32 v8, v216
	v_mov_b32_e32 v9, v217
	v_mov_b32_e32 v10, v218
	v_mov_b32_e32 v11, v219
	v_mov_b32_e32 v12, v220
	v_mov_b32_e32 v13, v221
	v_mov_b32_e32 v14, v222
	v_mov_b32_e32 v15, v223
	s_add_u32 s2, s9, s18
	s_cmp_eq_u32 s77, s2
	s_cbranch_scc1 .Lnm_f32_b0n
	s_cmpk_lt_u32 s2, 0x4000
	s_cbranch_scc0 .Lnm_math
	s_mov_b32 s77, s2
	s_lshl_b32 s2, s77, 12
	s_add_u32 s12, s82, s2
	s_addc_u32 s13, s83, 0
	global_load_dwordx4 v[224:227], v104, s[12:13] nt
	global_load_dwordx4 v[228:231], v104, s[12:13] offset:1024 nt
	global_load_dwordx4 v[232:235], v104, s[12:13] offset:2048 nt
	global_load_dwordx4 v[236:239], v104, s[12:13] offset:3072 nt
.Lnm_f32_b0n:
	s_add_u32 s76, s9, s18
	s_add_u32 s76, s76, s18
	s_cmpk_lt_u32 s76, 0x4000
	s_cbranch_scc0 .Lnm_math
	s_lshl_b32 s2, s76, 12
	s_add_u32 s12, s82, s2
	s_addc_u32 s13, s83, 0
	global_load_dwordx4 v[208:211], v104, s[12:13] nt
	global_load_dwordx4 v[212:215], v104, s[12:13] offset:1024 nt
	global_load_dwordx4 v[216:219], v104, s[12:13] offset:2048 nt
	global_load_dwordx4 v[220:223], v104, s[12:13] offset:3072 nt
	s_branch .Lnm_math

.Lnm_f32_b1:
	v_mov_b32_e32 v0, v224
	v_mov_b32_e32 v1, v225
	v_mov_b32_e32 v2, v226
	v_mov_b32_e32 v3, v227
	v_mov_b32_e32 v4, v228
	v_mov_b32_e32 v5, v229
	v_mov_b32_e32 v6, v230
	v_mov_b32_e32 v7, v231
	v_mov_b32_e32 v8, v232
	v_mov_b32_e32 v9, v233
	v_mov_b32_e32 v10, v234
	v_mov_b32_e32 v11, v235
	v_mov_b32_e32 v12, v236
	v_mov_b32_e32 v13, v237
	v_mov_b32_e32 v14, v238
	v_mov_b32_e32 v15, v239
	s_add_u32 s2, s9, s18
	s_cmp_eq_u32 s76, s2
	s_cbranch_scc1 .Lnm_f32_b1n
	s_cmpk_lt_u32 s2, 0x4000
	s_cbranch_scc0 .Lnm_math
	s_mov_b32 s76, s2
	s_lshl_b32 s2, s76, 12
	s_add_u32 s12, s82, s2
	s_addc_u32 s13, s83, 0
	global_load_dwordx4 v[208:211], v104, s[12:13] nt
	global_load_dwordx4 v[212:215], v104, s[12:13] offset:1024 nt
	global_load_dwordx4 v[216:219], v104, s[12:13] offset:2048 nt
	global_load_dwordx4 v[220:223], v104, s[12:13] offset:3072 nt
.Lnm_f32_b1n:
	s_add_u32 s77, s9, s18
	s_add_u32 s77, s77, s18
	s_cmpk_lt_u32 s77, 0x4000
	s_cbranch_scc0 .Lnm_math
	s_lshl_b32 s2, s77, 12
	s_add_u32 s12, s82, s2
	s_addc_u32 s13, s83, 0
	global_load_dwordx4 v[224:227], v104, s[12:13] nt
	global_load_dwordx4 v[228:231], v104, s[12:13] offset:1024 nt
	global_load_dwordx4 v[232:235], v104, s[12:13] offset:2048 nt
	global_load_dwordx4 v[236:239], v104, s[12:13] offset:3072 nt
	s_branch .Lnm_math
.Lnm_bf16row:
	s_cmp_eq_u32 s76, s9
	s_cbranch_scc1 .Lnm_b16_b0w
	s_cmp_eq_u32 s77, s9
	s_cbranch_scc1 .Lnm_b16_b1w
	s_lshl_b32 s2, s9, 11
	s_add_u32 s12, s84, s2
	s_addc_u32 s13, s85, 0
	global_load_dwordx2 v[208:209], v105, s[12:13]
	global_load_dwordx2 v[210:211], v105, s[12:13] offset:512
	global_load_dwordx2 v[212:213], v105, s[12:13] offset:1024
	global_load_dwordx2 v[214:215], v105, s[12:13] offset:1536
	s_mov_b32 s76, s9
	s_waitcnt vmcnt(0)
	s_branch .Lnm_b16_b0

.Lnm_b16_b0:
	v_lshlrev_b32_e32 v0, 16, v208
	v_and_b32_e32 v1, 0xffff0000, v208
	v_lshlrev_b32_e32 v2, 16, v209
	v_and_b32_e32 v3, 0xffff0000, v209
	v_lshlrev_b32_e32 v4, 16, v210
	v_and_b32_e32 v5, 0xffff0000, v210
	v_lshlrev_b32_e32 v6, 16, v211
	v_and_b32_e32 v7, 0xffff0000, v211
	v_lshlrev_b32_e32 v8, 16, v212
	v_and_b32_e32 v9, 0xffff0000, v212
	v_lshlrev_b32_e32 v10, 16, v213
	v_and_b32_e32 v11, 0xffff0000, v213
	v_lshlrev_b32_e32 v12, 16, v214
	v_and_b32_e32 v13, 0xffff0000, v214
	v_lshlrev_b32_e32 v14, 16, v215
	v_and_b32_e32 v15, 0xffff0000, v215
	s_add_u32 s2, s9, s18
	s_cmp_eq_u32 s77, s2
	s_cbranch_scc1 .Lnm_b16_b0n
	s_cmpk_lt_u32 s2, 0x4000
	s_cbranch_scc0 .Lnm_math
	s_mov_b32 s77, s2
	s_lshl_b32 s2, s77, 11
	s_add_u32 s12, s84, s2
	s_addc_u32 s13, s85, 0
	global_load_dwordx2 v[224:225], v105, s[12:13]
	global_load_dwordx2 v[226:227], v105, s[12:13] offset:512
	global_load_dwordx2 v[228:229], v105, s[12:13] offset:1024
	global_load_dwordx2 v[230:231], v105, s[12:13] offset:1536
.Lnm_b16_b0n:
	s_add_u32 s76, s9, s18
	s_add_u32 s76, s76, s18
	s_cmpk_lt_u32 s76, 0x4000
	s_cbranch_scc0 .Lnm_math
	s_lshl_b32 s2, s76, 11
	s_add_u32 s12, s84, s2
	s_addc_u32 s13, s85, 0
	global_load_dwordx2 v[208:209], v105, s[12:13]
	global_load_dwordx2 v[210:211], v105, s[12:13] offset:512
	global_load_dwordx2 v[212:213], v105, s[12:13] offset:1024
	global_load_dwordx2 v[214:215], v105, s[12:13] offset:1536
	s_branch .Lnm_math

.Lnm_b16_b1:
	v_lshlrev_b32_e32 v0, 16, v224
	v_and_b32_e32 v1, 0xffff0000, v224
	v_lshlrev_b32_e32 v2, 16, v225
	v_and_b32_e32 v3, 0xffff0000, v225
	v_lshlrev_b32_e32 v4, 16, v226
	v_and_b32_e32 v5, 0xffff0000, v226
	v_lshlrev_b32_e32 v6, 16, v227
	v_and_b32_e32 v7, 0xffff0000, v227
	v_lshlrev_b32_e32 v8, 16, v228
	v_and_b32_e32 v9, 0xffff0000, v228
	v_lshlrev_b32_e32 v10, 16, v229
	v_and_b32_e32 v11, 0xffff0000, v229
	v_lshlrev_b32_e32 v12, 16, v230
	v_and_b32_e32 v13, 0xffff0000, v230
	v_lshlrev_b32_e32 v14, 16, v231
	v_and_b32_e32 v15, 0xffff0000, v231
	s_add_u32 s2, s9, s18
	s_cmp_eq_u32 s76, s2
	s_cbranch_scc1 .Lnm_b16_b1n
	s_cmpk_lt_u32 s2, 0x4000
	s_cbranch_scc0 .Lnm_math
	s_mov_b32 s76, s2
	s_lshl_b32 s2, s76, 11
	s_add_u32 s12, s84, s2
	s_addc_u32 s13, s85, 0
	global_load_dwordx2 v[208:209], v105, s[12:13]
	global_load_dwordx2 v[210:211], v105, s[12:13] offset:512
	global_load_dwordx2 v[212:213], v105, s[12:13] offset:1024
	global_load_dwordx2 v[214:215], v105, s[12:13] offset:1536
.Lnm_b16_b1n:
	s_add_u32 s77, s9, s18
	s_add_u32 s77, s77, s18
	s_cmpk_lt_u32 s77, 0x4000
	s_cbranch_scc0 .Lnm_math
	s_lshl_b32 s2, s77, 11
	s_add_u32 s12, s84, s2
	s_addc_u32 s13, s85, 0
	global_load_dwordx2 v[224:225], v105, s[12:13]
	global_load_dwordx2 v[226:227], v105, s[12:13] offset:512
	global_load_dwordx2 v[228:229], v105, s[12:13] offset:1024
	global_load_dwordx2 v[230:231], v105, s[12:13] offset:1536
	s_branch .Lnm_math
